# grid barrier: invalidate hoisted before polling (last arriver: after its TOP atomic), all workgroups poll the global generation word
# speedup vs baseline: 1.0291x; 1.0154x over previous
.LBB0_595:
	s_or_b64 exec, exec, s[4:5]
	v_cvt_f32_u32_e32 v4, v2
	s_waitcnt vmcnt(0)
	v_readfirstlane_b32 s4, v3
	v_sub_u32_e32 v3, 0, v2
	v_rcp_iflag_f32_e32 v4, v4
	v_add_u32_e32 v5, s4, v1
	v_mul_f32_e32 v4, 0x4f7ffffe, v4
	v_cvt_u32_f32_e32 v4, v4
	v_mul_lo_u32 v1, v3, v4
	v_mul_hi_u32 v1, v4, v1
	v_add_u32_e32 v1, v4, v1
	v_mul_hi_u32 v1, v5, v1
	v_mul_lo_u32 v3, v1, v2
	v_sub_u32_e32 v3, v5, v3
	v_add_u32_e32 v4, 1, v1
	v_cmp_ge_u32_e32 vcc, v3, v2
	s_nop 1
	v_cndmask_b32_e32 v1, v1, v4, vcc
	v_sub_u32_e32 v4, v3, v2
	v_cndmask_b32_e32 v3, v3, v4, vcc
	v_add_u32_e32 v4, 1, v1
	v_cmp_ge_u32_e32 vcc, v3, v2
	v_add_u32_e32 v3, 1, v5
	s_nop 0
	v_cndmask_b32_e32 v1, v1, v4, vcc
	v_mul_lo_u32 v4, v2, v1
	v_add_u32_e32 v2, v4, v2
	v_cmp_ne_u32_e32 vcc, v3, v2
	s_and_saveexec_b64 s[4:5], vcc
	s_xor_b64 s[4:5], exec, s[4:5]
	s_cbranch_execz .LBB0_609
	buffer_inv sc1
	v_readlane_b32 s6, v254, 42
	v_readlane_b32 s7, v254, 43
	s_waitcnt lgkmcnt(0)
	s_nop 3
	global_load_dword v0, v81, s[6:7] sc1
	s_waitcnt vmcnt(0)
	v_cmp_eq_u32_e32 vcc, v0, v1
	s_and_saveexec_b64 s[6:7], vcc
	s_cbranch_execz .LBB0_608
	s_mov_b64 s[26:27], s[22:23]
	s_mov_b32 s18, 1
	s_mov_b64 s[8:9], 0
	s_branch .LBB0_599

.LBB0_603:
	v_readlane_b32 s14, v254, 42
	v_readlane_b32 s15, v254, 43
	s_add_i32 s18, s18, 1
	s_mov_b64 s[16:17], -1
	s_nop 2
	global_load_dword v0, v81, s[14:15] sc1
	s_waitcnt vmcnt(0)
	v_cmp_ne_u32_e32 vcc, v0, v1
	s_orn2_b64 s[14:15], vcc, exec
	s_branch .LBB0_598

.LBB0_612:
	s_or_b64 exec, exec, s[6:7]
	s_waitcnt vmcnt(0)
	v_readfirstlane_b32 s4, v2
	buffer_inv sc1
	v_cvt_f32_u32_e32 v2, v0
	v_sub_u32_e32 v3, 0, v0
	v_add_u32_e32 v1, s4, v1
	v_readlane_b32 s4, v254, 42
	v_rcp_iflag_f32_e32 v2, v2
	v_readlane_b32 s5, v254, 43
	s_mov_b64 s[6:7], -1
	v_mul_f32_e32 v2, 0x4f7ffffe, v2
	v_cvt_u32_f32_e32 v2, v2
	v_mul_lo_u32 v3, v3, v2
	v_mul_hi_u32 v3, v2, v3
	v_add_u32_e32 v2, v2, v3
	v_mul_hi_u32 v2, v1, v2
	v_mul_lo_u32 v3, v2, v0
	v_sub_u32_e32 v3, v1, v3
	v_cmp_ge_u32_e32 vcc, v3, v0
	v_add_u32_e32 v4, 1, v2
	v_add_u32_e32 v1, 1, v1
	v_cndmask_b32_e32 v2, v2, v4, vcc
	v_sub_u32_e32 v4, v3, v0
	v_cndmask_b32_e32 v3, v3, v4, vcc
	v_cmp_ge_u32_e32 vcc, v3, v0
	v_add_u32_e32 v3, 1, v2
	s_nop 0
	v_cndmask_b32_e32 v2, v2, v3, vcc
	v_mul_lo_u32 v3, v0, v2
	v_add_u32_e32 v0, v3, v0
	v_cmp_ne_u32_e32 vcc, v1, v0
	v_mov_b64_e32 v[0:1], s[4:5]
	s_and_saveexec_b64 s[4:5], vcc
	s_cbranch_execz .LBB0_624
	v_readlane_b32 s6, v254, 42
	v_readlane_b32 s7, v254, 43
	s_mov_b64 s[8:9], 0
	s_nop 3
	global_load_dword v0, v81, s[6:7] sc1
	s_waitcnt vmcnt(0)
	v_cmp_eq_u32_e32 vcc, v0, v2
	s_and_saveexec_b64 s[6:7], vcc
	s_cbranch_execz .LBB0_623
	s_mov_b64 s[26:27], s[22:23]
	s_mov_b32 s18, 1
	s_branch .LBB0_616
